# prep step 4: forward substitution moved to f32 matrix cores (16x16x4 f32 MFMA, blocked, diagonal blocks inverted on the VALU)
# speedup vs baseline: 1.0411x; 1.0216x over previous
.LBB0_339:
	s_andn2_b64 vcc, exec, s[28:29]
	s_cbranch_vccnz .LBB0_174
	v_cndmask_b32_e64 v2, v240, v238, s[48:49]
	v_add_u32_e32 v169, v2, v235
	v_cndmask_b32_e64 v2, v28, v238, s[48:49]
	v_add_u32_e32 v167, v2, v235
	v_lshl_add_u32 v239, s20, 2, v239
	s_setprio 2
	v_and_b32_e32 v128, 15, v160
	v_lshrrev_b32_e32 v121, 4, v160
	v_lshl_add_u32 v169, v121, 11, v169
	v_lshl_add_u32 v167, v121, 11, v167
	v_lshl_add_u32 v239, v121, 4, v239
	v_mul_u32_u24_e32 v2, 0x110, v128
	v_lshl_add_u32 v2, v121, 4, v2
	v_add_u32_e32 v2, v2, v234
	v_mul_u32_u24_e32 v129, 0x1140, v121
	v_add_u32_e32 v129, v129, v234
	s_lshl_b32 s28, s88, 7
	s_addk_i32 s28, 0x4400
	v_lshl_add_u32 v3, v121, 10, s28
	v_lshl_add_u32 v3, v128, 2, v3
	v_add_u32_e32 v3, v3, v234
	v_lshl_add_u32 v120, v128, 6, s28
	v_lshl_add_u32 v120, v121, 4, v120
	v_add_u32_e32 v120, v120, v234
	v_cmp_eq_u32_e32 vcc, 0, v128
	s_nop 1
	v_cndmask_b32_e64 v88, 0, -1.0, vcc
	v_cmp_eq_u32_e32 vcc, 1, v128
	s_nop 1
	v_cndmask_b32_e64 v89, 0, -1.0, vcc
	v_cmp_eq_u32_e32 vcc, 2, v128
	s_nop 1
	v_cndmask_b32_e64 v90, 0, -1.0, vcc
	v_cmp_eq_u32_e32 vcc, 3, v128
	s_nop 1
	v_cndmask_b32_e64 v91, 0, -1.0, vcc
	v_cmp_eq_u32_e32 vcc, 4, v128
	s_nop 1
	v_cndmask_b32_e64 v92, 0, -1.0, vcc
	v_cmp_eq_u32_e32 vcc, 5, v128
	s_nop 1
	v_cndmask_b32_e64 v93, 0, -1.0, vcc
	v_cmp_eq_u32_e32 vcc, 6, v128
	s_nop 1
	v_cndmask_b32_e64 v94, 0, -1.0, vcc
	v_cmp_eq_u32_e32 vcc, 7, v128
	s_nop 1
	v_cndmask_b32_e64 v95, 0, -1.0, vcc
	v_cmp_eq_u32_e32 vcc, 8, v128
	s_nop 1
	v_cndmask_b32_e64 v96, 0, -1.0, vcc
	v_cmp_eq_u32_e32 vcc, 9, v128
	s_nop 1
	v_cndmask_b32_e64 v97, 0, -1.0, vcc
	v_cmp_eq_u32_e32 vcc, 10, v128
	s_nop 1
	v_cndmask_b32_e64 v98, 0, -1.0, vcc
	v_cmp_eq_u32_e32 vcc, 11, v128
	s_nop 1
	v_cndmask_b32_e64 v99, 0, -1.0, vcc
	v_cmp_eq_u32_e32 vcc, 12, v128
	s_nop 1
	v_cndmask_b32_e64 v100, 0, -1.0, vcc
	v_cmp_eq_u32_e32 vcc, 13, v128
	s_nop 1
	v_cndmask_b32_e64 v101, 0, -1.0, vcc
	v_cmp_eq_u32_e32 vcc, 14, v128
	s_nop 1
	v_cndmask_b32_e64 v102, 0, -1.0, vcc
	v_cmp_eq_u32_e32 vcc, 15, v128
	s_nop 1
	v_cndmask_b32_e64 v103, 0, -1.0, vcc
	ds_read_b128 v[104:107], v129 offset:272
	ds_read_b128 v[108:111], v129 offset:544
	ds_read_b128 v[112:115], v129 offset:816
	ds_read_b128 v[116:119], v129 offset:1088
	s_waitcnt lgkmcnt(3)
	v_fma_f32 v89, -v104, v88, v89
	ds_read_b128 v[104:107], v129 offset:1360
	s_waitcnt lgkmcnt(3)
	v_fma_f32 v90, -v108, v88, v90
	v_fma_f32 v90, -v109, v89, v90
	ds_read_b128 v[108:111], v129 offset:1376
	s_waitcnt lgkmcnt(3)
	v_fma_f32 v91, -v112, v88, v91
	v_fma_f32 v91, -v113, v89, v91
	v_fma_f32 v91, -v114, v90, v91
	ds_read_b128 v[112:115], v129 offset:1632
	s_waitcnt lgkmcnt(3)
	v_fma_f32 v92, -v116, v88, v92
	v_fma_f32 v92, -v117, v89, v92
	v_fma_f32 v92, -v118, v90, v92
	v_fma_f32 v92, -v119, v91, v92
	ds_read_b128 v[116:119], v129 offset:1648
	s_waitcnt lgkmcnt(3)
	v_fma_f32 v93, -v104, v88, v93
	v_fma_f32 v93, -v105, v89, v93
	v_fma_f32 v93, -v106, v90, v93
	v_fma_f32 v93, -v107, v91, v93
	ds_read_b128 v[104:107], v129 offset:1904
	s_waitcnt lgkmcnt(3)
	v_fma_f32 v93, -v108, v92, v93
	ds_read_b128 v[108:111], v129 offset:1920
	s_waitcnt lgkmcnt(3)
	v_fma_f32 v94, -v112, v88, v94
	v_fma_f32 v94, -v113, v89, v94
	v_fma_f32 v94, -v114, v90, v94
	v_fma_f32 v94, -v115, v91, v94
	ds_read_b128 v[112:115], v129 offset:2176
	s_waitcnt lgkmcnt(3)
	v_fma_f32 v94, -v116, v92, v94
	v_fma_f32 v94, -v117, v93, v94
	ds_read_b128 v[116:119], v129 offset:2192
	s_waitcnt lgkmcnt(3)
	v_fma_f32 v95, -v104, v88, v95
	v_fma_f32 v95, -v105, v89, v95
	v_fma_f32 v95, -v106, v90, v95
	v_fma_f32 v95, -v107, v91, v95
	ds_read_b128 v[104:107], v129 offset:2448
	s_waitcnt lgkmcnt(3)
	v_fma_f32 v95, -v108, v92, v95
	v_fma_f32 v95, -v109, v93, v95
	v_fma_f32 v95, -v110, v94, v95
	ds_read_b128 v[108:111], v129 offset:2464
	s_waitcnt lgkmcnt(3)
	v_fma_f32 v96, -v112, v88, v96
	v_fma_f32 v96, -v113, v89, v96
	v_fma_f32 v96, -v114, v90, v96
	v_fma_f32 v96, -v115, v91, v96
	ds_read_b128 v[112:115], v129 offset:2480
	s_waitcnt lgkmcnt(3)
	v_fma_f32 v96, -v116, v92, v96
	v_fma_f32 v96, -v117, v93, v96
	v_fma_f32 v96, -v118, v94, v96
	v_fma_f32 v96, -v119, v95, v96
	ds_read_b128 v[116:119], v129 offset:2720
	s_waitcnt lgkmcnt(3)
	v_fma_f32 v97, -v104, v88, v97
	v_fma_f32 v97, -v105, v89, v97
	v_fma_f32 v97, -v106, v90, v97
	v_fma_f32 v97, -v107, v91, v97
	ds_read_b128 v[104:107], v129 offset:2736
	s_waitcnt lgkmcnt(3)
	v_fma_f32 v97, -v108, v92, v97
	v_fma_f32 v97, -v109, v93, v97
	v_fma_f32 v97, -v110, v94, v97
	v_fma_f32 v97, -v111, v95, v97
	ds_read_b128 v[108:111], v129 offset:2752
	s_waitcnt lgkmcnt(3)
	v_fma_f32 v97, -v112, v96, v97
	ds_read_b128 v[112:115], v129 offset:2992
	s_waitcnt lgkmcnt(3)
	v_fma_f32 v98, -v116, v88, v98
	v_fma_f32 v98, -v117, v89, v98
	v_fma_f32 v98, -v118, v90, v98
	v_fma_f32 v98, -v119, v91, v98
	ds_read_b128 v[116:119], v129 offset:3008
	s_waitcnt lgkmcnt(3)
	v_fma_f32 v98, -v104, v92, v98
	v_fma_f32 v98, -v105, v93, v98
	v_fma_f32 v98, -v106, v94, v98
	v_fma_f32 v98, -v107, v95, v98
	ds_read_b128 v[104:107], v129 offset:3024
	s_waitcnt lgkmcnt(3)
	v_fma_f32 v98, -v108, v96, v98
	v_fma_f32 v98, -v109, v97, v98
	ds_read_b128 v[108:111], v129 offset:3264
	s_waitcnt lgkmcnt(3)
	v_fma_f32 v99, -v112, v88, v99
	v_fma_f32 v99, -v113, v89, v99
	v_fma_f32 v99, -v114, v90, v99
	v_fma_f32 v99, -v115, v91, v99
	ds_read_b128 v[112:115], v129 offset:3280
	s_waitcnt lgkmcnt(3)
	v_fma_f32 v99, -v116, v92, v99
	v_fma_f32 v99, -v117, v93, v99
	v_fma_f32 v99, -v118, v94, v99
	v_fma_f32 v99, -v119, v95, v99
	ds_read_b128 v[116:119], v129 offset:3296
	s_waitcnt lgkmcnt(3)
	v_fma_f32 v99, -v104, v96, v99
	v_fma_f32 v99, -v105, v97, v99
	v_fma_f32 v99, -v106, v98, v99
	ds_read_b128 v[104:107], v129 offset:3536
	s_waitcnt lgkmcnt(3)
	v_fma_f32 v100, -v108, v88, v100
	v_fma_f32 v100, -v109, v89, v100
	v_fma_f32 v100, -v110, v90, v100
	v_fma_f32 v100, -v111, v91, v100
	ds_read_b128 v[108:111], v129 offset:3552
	s_waitcnt lgkmcnt(3)
	v_fma_f32 v100, -v112, v92, v100
	v_fma_f32 v100, -v113, v93, v100
	v_fma_f32 v100, -v114, v94, v100
	v_fma_f32 v100, -v115, v95, v100
	ds_read_b128 v[112:115], v129 offset:3568
	s_waitcnt lgkmcnt(3)
	v_fma_f32 v100, -v116, v96, v100
	v_fma_f32 v100, -v117, v97, v100
	v_fma_f32 v100, -v118, v98, v100
	v_fma_f32 v100, -v119, v99, v100
	ds_read_b128 v[116:119], v129 offset:3584
	s_waitcnt lgkmcnt(3)
	v_fma_f32 v101, -v104, v88, v101
	v_fma_f32 v101, -v105, v89, v101
	v_fma_f32 v101, -v106, v90, v101
	v_fma_f32 v101, -v107, v91, v101
	ds_read_b128 v[104:107], v129 offset:3808
	s_waitcnt lgkmcnt(3)
	v_fma_f32 v101, -v108, v92, v101
	v_fma_f32 v101, -v109, v93, v101
	v_fma_f32 v101, -v110, v94, v101
	v_fma_f32 v101, -v111, v95, v101
	ds_read_b128 v[108:111], v129 offset:3824
	s_waitcnt lgkmcnt(3)
	v_fma_f32 v101, -v112, v96, v101
	v_fma_f32 v101, -v113, v97, v101
	v_fma_f32 v101, -v114, v98, v101
	v_fma_f32 v101, -v115, v99, v101
	ds_read_b128 v[112:115], v129 offset:3840
	s_waitcnt lgkmcnt(3)
	v_fma_f32 v101, -v116, v100, v101
	ds_read_b128 v[116:119], v129 offset:3856
	s_waitcnt lgkmcnt(3)
	v_fma_f32 v102, -v104, v88, v102
	v_fma_f32 v102, -v105, v89, v102
	v_fma_f32 v102, -v106, v90, v102
	v_fma_f32 v102, -v107, v91, v102
	ds_read_b128 v[104:107], v129 offset:4080
	s_waitcnt lgkmcnt(3)
	v_fma_f32 v102, -v108, v92, v102
	v_fma_f32 v102, -v109, v93, v102
	v_fma_f32 v102, -v110, v94, v102
	v_fma_f32 v102, -v111, v95, v102
	ds_read_b128 v[108:111], v129 offset:4096
	s_waitcnt lgkmcnt(3)
	v_fma_f32 v102, -v112, v96, v102
	v_fma_f32 v102, -v113, v97, v102
	v_fma_f32 v102, -v114, v98, v102
	v_fma_f32 v102, -v115, v99, v102
	ds_read_b128 v[112:115], v129 offset:4112
	s_waitcnt lgkmcnt(3)
	v_fma_f32 v102, -v116, v100, v102
	v_fma_f32 v102, -v117, v101, v102
	ds_read_b128 v[116:119], v129 offset:4128
	s_waitcnt lgkmcnt(3)
	v_fma_f32 v103, -v104, v88, v103
	v_fma_f32 v103, -v105, v89, v103
	v_fma_f32 v103, -v106, v90, v103
	v_fma_f32 v103, -v107, v91, v103
	s_waitcnt lgkmcnt(2)
	v_fma_f32 v103, -v108, v92, v103
	v_fma_f32 v103, -v109, v93, v103
	v_fma_f32 v103, -v110, v94, v103
	v_fma_f32 v103, -v111, v95, v103
	s_waitcnt lgkmcnt(1)
	v_fma_f32 v103, -v112, v96, v103
	v_fma_f32 v103, -v113, v97, v103
	v_fma_f32 v103, -v114, v98, v103
	v_fma_f32 v103, -v115, v99, v103
	s_waitcnt lgkmcnt(0)
	v_fma_f32 v103, -v116, v100, v103
	v_fma_f32 v103, -v117, v101, v103
	v_fma_f32 v103, -v118, v102, v103
	ds_write_b32 v3, v88 offset:0
	ds_write_b32 v3, v89 offset:64
	ds_write_b32 v3, v90 offset:128
	ds_write_b32 v3, v91 offset:192
	ds_write_b32 v3, v92 offset:256
	ds_write_b32 v3, v93 offset:320
	ds_write_b32 v3, v94 offset:384
	ds_write_b32 v3, v95 offset:448
	ds_write_b32 v3, v96 offset:512
	ds_write_b32 v3, v97 offset:576
	ds_write_b32 v3, v98 offset:640
	ds_write_b32 v3, v99 offset:704
	ds_write_b32 v3, v100 offset:768
	ds_write_b32 v3, v101 offset:832
	ds_write_b32 v3, v102 offset:896
	ds_write_b32 v3, v103 offset:960
	ds_read_b128 v[170:173], v120 offset:0
	ds_read_b128 v[174:177], v120 offset:1024
	ds_read_b128 v[178:181], v120 offset:2048
	ds_read_b128 v[188:191], v120 offset:3072
	ds_read_b128 v[124:127], v239 offset:0
	ds_read_b32 v88, v169 offset:0
	ds_read_b32 v89, v169 offset:528
	ds_read_b32 v90, v169 offset:1056
	ds_read_b32 v91, v169 offset:1584
	ds_read_b32 v92, v169 offset:64
	ds_read_b32 v93, v169 offset:592
	ds_read_b32 v94, v169 offset:1120
	ds_read_b32 v95, v169 offset:1648
	ds_read_b32 v96, v169 offset:128
	ds_read_b32 v97, v169 offset:656
	ds_read_b32 v98, v169 offset:1184
	ds_read_b32 v99, v169 offset:1712
	ds_read_b32 v100, v169 offset:192
	ds_read_b32 v101, v169 offset:720
	ds_read_b32 v102, v169 offset:1248
	ds_read_b32 v103, v169 offset:1776
	s_waitcnt lgkmcnt(0)
	v_mul_f32_e64 v88, -v124, v88
	v_mul_f32_e64 v89, -v125, v89
	v_mul_f32_e64 v90, -v126, v90
	v_mul_f32_e64 v91, -v127, v91
	v_mul_f32_e64 v92, -v124, v92
	v_mul_f32_e64 v93, -v125, v93
	v_mul_f32_e64 v94, -v126, v94
	v_mul_f32_e64 v95, -v127, v95
	v_mul_f32_e64 v96, -v124, v96
	v_mul_f32_e64 v97, -v125, v97
	v_mul_f32_e64 v98, -v126, v98
	v_mul_f32_e64 v99, -v127, v99
	v_mul_f32_e64 v100, -v124, v100
	v_mul_f32_e64 v101, -v125, v101
	v_mul_f32_e64 v102, -v126, v102
	v_mul_f32_e64 v103, -v127, v103
	ds_read_b128 v[192:195], v239 offset:64
	ds_read_b32 v104, v169 offset:8448
	ds_read_b32 v105, v169 offset:8976
	ds_read_b32 v106, v169 offset:9504
	ds_read_b32 v107, v169 offset:10032
	ds_read_b32 v108, v169 offset:8512
	ds_read_b32 v109, v169 offset:9040
	ds_read_b32 v110, v169 offset:9568
	ds_read_b32 v111, v169 offset:10096
	ds_read_b32 v112, v169 offset:8576
	ds_read_b32 v113, v169 offset:9104
	ds_read_b32 v114, v169 offset:9632
	ds_read_b32 v115, v169 offset:10160
	ds_read_b32 v116, v169 offset:8640
	ds_read_b32 v117, v169 offset:9168
	ds_read_b32 v118, v169 offset:9696
	ds_read_b32 v119, v169 offset:10224
	s_nop 9
	v_mfma_f32_16x16x4_f32 v[30:33], v170, v88, 0
	v_mfma_f32_16x16x4_f32 v[30:33], v171, v89, v[30:33]
	v_mfma_f32_16x16x4_f32 v[30:33], v172, v90, v[30:33]
	v_mfma_f32_16x16x4_f32 v[30:33], v173, v91, v[30:33]
	v_mfma_f32_16x16x4_f32 v[34:37], v170, v92, 0
	v_mfma_f32_16x16x4_f32 v[34:37], v171, v93, v[34:37]
	v_mfma_f32_16x16x4_f32 v[34:37], v172, v94, v[34:37]
	v_mfma_f32_16x16x4_f32 v[34:37], v173, v95, v[34:37]
	v_mfma_f32_16x16x4_f32 v[38:41], v170, v96, 0
	v_mfma_f32_16x16x4_f32 v[38:41], v171, v97, v[38:41]
	v_mfma_f32_16x16x4_f32 v[38:41], v172, v98, v[38:41]
	v_mfma_f32_16x16x4_f32 v[38:41], v173, v99, v[38:41]
	v_mfma_f32_16x16x4_f32 v[42:45], v170, v100, 0
	v_mfma_f32_16x16x4_f32 v[42:45], v171, v101, v[42:45]
	v_mfma_f32_16x16x4_f32 v[42:45], v172, v102, v[42:45]
	v_mfma_f32_16x16x4_f32 v[42:45], v173, v103, v[42:45]
	s_nop 9
	ds_write_b32 v167, v30 offset:0
	ds_write_b32 v167, v31 offset:528
	ds_write_b32 v167, v32 offset:1056
	ds_write_b32 v167, v33 offset:1584
	ds_write_b32 v167, v34 offset:64
	ds_write_b32 v167, v35 offset:592
	ds_write_b32 v167, v36 offset:1120
	ds_write_b32 v167, v37 offset:1648
	ds_write_b32 v167, v38 offset:128
	ds_write_b32 v167, v39 offset:656
	ds_write_b32 v167, v40 offset:1184
	ds_write_b32 v167, v41 offset:1712
	ds_write_b32 v167, v42 offset:192
	ds_write_b32 v167, v43 offset:720
	ds_write_b32 v167, v44 offset:1248
	ds_write_b32 v167, v45 offset:1776
	s_waitcnt lgkmcnt(0)
	v_mul_f32_e64 v104, -v192, v104
	v_mul_f32_e64 v105, -v193, v105
	v_mul_f32_e64 v106, -v194, v106
	v_mul_f32_e64 v107, -v195, v107
	v_mul_f32_e64 v108, -v192, v108
	v_mul_f32_e64 v109, -v193, v109
	v_mul_f32_e64 v110, -v194, v110
	v_mul_f32_e64 v111, -v195, v111
	v_mul_f32_e64 v112, -v192, v112
	v_mul_f32_e64 v113, -v193, v113
	v_mul_f32_e64 v114, -v194, v114
	v_mul_f32_e64 v115, -v195, v115
	v_mul_f32_e64 v116, -v192, v116
	v_mul_f32_e64 v117, -v193, v117
	v_mul_f32_e64 v118, -v194, v118
	v_mul_f32_e64 v119, -v195, v119
	ds_read_b128 v[124:127], v239 offset:128
	ds_read_b128 v[20:23], v2 offset:4352
	ds_read_b32 v88, v169 offset:16896
	ds_read_b32 v89, v169 offset:17424
	ds_read_b32 v90, v169 offset:17952
	ds_read_b32 v91, v169 offset:18480
	ds_read_b32 v92, v169 offset:16960
	ds_read_b32 v93, v169 offset:17488
	ds_read_b32 v94, v169 offset:18016
	ds_read_b32 v95, v169 offset:18544
	ds_read_b32 v96, v169 offset:17024
	ds_read_b32 v97, v169 offset:17552
	ds_read_b32 v98, v169 offset:18080
	ds_read_b32 v99, v169 offset:18608
	ds_read_b32 v100, v169 offset:17088
	ds_read_b32 v101, v169 offset:17616
	ds_read_b32 v102, v169 offset:18144
	ds_read_b32 v103, v169 offset:18672
	s_waitcnt lgkmcnt(15)
	v_mfma_f32_16x16x4_f32 v[104:107], v20, v30, v[104:107]
	v_mfma_f32_16x16x4_f32 v[108:111], v20, v34, v[108:111]
	v_mfma_f32_16x16x4_f32 v[112:115], v20, v38, v[112:115]
	v_mfma_f32_16x16x4_f32 v[116:119], v20, v42, v[116:119]
	v_mfma_f32_16x16x4_f32 v[104:107], v21, v31, v[104:107]
	v_mfma_f32_16x16x4_f32 v[108:111], v21, v35, v[108:111]
	v_mfma_f32_16x16x4_f32 v[112:115], v21, v39, v[112:115]
	v_mfma_f32_16x16x4_f32 v[116:119], v21, v43, v[116:119]
	v_mfma_f32_16x16x4_f32 v[104:107], v22, v32, v[104:107]
	v_mfma_f32_16x16x4_f32 v[108:111], v22, v36, v[108:111]
	v_mfma_f32_16x16x4_f32 v[112:115], v22, v40, v[112:115]
	v_mfma_f32_16x16x4_f32 v[116:119], v22, v44, v[116:119]
	v_mfma_f32_16x16x4_f32 v[104:107], v23, v33, v[104:107]
	v_mfma_f32_16x16x4_f32 v[108:111], v23, v37, v[108:111]
	v_mfma_f32_16x16x4_f32 v[112:115], v23, v41, v[112:115]
	v_mfma_f32_16x16x4_f32 v[116:119], v23, v45, v[116:119]
	s_nop 9
	v_mfma_f32_16x16x4_f32 v[46:49], v174, v104, 0
	v_mfma_f32_16x16x4_f32 v[46:49], v175, v105, v[46:49]
	v_mfma_f32_16x16x4_f32 v[46:49], v176, v106, v[46:49]
	v_mfma_f32_16x16x4_f32 v[46:49], v177, v107, v[46:49]
	v_mfma_f32_16x16x4_f32 v[50:53], v174, v108, 0
	v_mfma_f32_16x16x4_f32 v[50:53], v175, v109, v[50:53]
	v_mfma_f32_16x16x4_f32 v[50:53], v176, v110, v[50:53]
	v_mfma_f32_16x16x4_f32 v[50:53], v177, v111, v[50:53]
	v_mfma_f32_16x16x4_f32 v[54:57], v174, v112, 0
	v_mfma_f32_16x16x4_f32 v[54:57], v175, v113, v[54:57]
	v_mfma_f32_16x16x4_f32 v[54:57], v176, v114, v[54:57]
	v_mfma_f32_16x16x4_f32 v[54:57], v177, v115, v[54:57]
	v_mfma_f32_16x16x4_f32 v[58:61], v174, v116, 0
	v_mfma_f32_16x16x4_f32 v[58:61], v175, v117, v[58:61]
	v_mfma_f32_16x16x4_f32 v[58:61], v176, v118, v[58:61]
	v_mfma_f32_16x16x4_f32 v[58:61], v177, v119, v[58:61]
	s_nop 9
	ds_write_b32 v167, v46 offset:8448
	ds_write_b32 v167, v47 offset:8976
	ds_write_b32 v167, v48 offset:9504
	ds_write_b32 v167, v49 offset:10032
	ds_write_b32 v167, v50 offset:8512
	ds_write_b32 v167, v51 offset:9040
	ds_write_b32 v167, v52 offset:9568
	ds_write_b32 v167, v53 offset:10096
	ds_write_b32 v167, v54 offset:8576
	ds_write_b32 v167, v55 offset:9104
	ds_write_b32 v167, v56 offset:9632
	ds_write_b32 v167, v57 offset:10160
	ds_write_b32 v167, v58 offset:8640
	ds_write_b32 v167, v59 offset:9168
	ds_write_b32 v167, v60 offset:9696
	ds_write_b32 v167, v61 offset:10224
	s_waitcnt lgkmcnt(0)
	v_mul_f32_e64 v88, -v124, v88
	v_mul_f32_e64 v89, -v125, v89
	v_mul_f32_e64 v90, -v126, v90
	v_mul_f32_e64 v91, -v127, v91
	v_mul_f32_e64 v92, -v124, v92
	v_mul_f32_e64 v93, -v125, v93
	v_mul_f32_e64 v94, -v126, v94
	v_mul_f32_e64 v95, -v127, v95
	v_mul_f32_e64 v96, -v124, v96
	v_mul_f32_e64 v97, -v125, v97
	v_mul_f32_e64 v98, -v126, v98
	v_mul_f32_e64 v99, -v127, v99
	v_mul_f32_e64 v100, -v124, v100
	v_mul_f32_e64 v101, -v125, v101
	v_mul_f32_e64 v102, -v126, v102
	v_mul_f32_e64 v103, -v127, v103
	ds_read_b128 v[192:195], v239 offset:192
	ds_read_b128 v[20:23], v2 offset:8704
	ds_read_b128 v[24:27], v2 offset:8768
	ds_read_b32 v104, v169 offset:25344
	ds_read_b32 v105, v169 offset:25872
	ds_read_b32 v106, v169 offset:26400
	ds_read_b32 v107, v169 offset:26928
	ds_read_b32 v108, v169 offset:25408
	ds_read_b32 v109, v169 offset:25936
	ds_read_b32 v110, v169 offset:26464
	ds_read_b32 v111, v169 offset:26992
	ds_read_b32 v112, v169 offset:25472
	ds_read_b32 v113, v169 offset:26000
	ds_read_b32 v114, v169 offset:26528
	ds_read_b32 v115, v169 offset:27056
	ds_read_b32 v116, v169 offset:25536
	ds_read_b32 v117, v169 offset:26064
	ds_read_b32 v118, v169 offset:26592
	ds_read_b32 v119, v169 offset:27120
	s_waitcnt lgkmcnt(15)
	v_mfma_f32_16x16x4_f32 v[88:91], v20, v30, v[88:91]
	v_mfma_f32_16x16x4_f32 v[92:95], v20, v34, v[92:95]
	v_mfma_f32_16x16x4_f32 v[96:99], v20, v38, v[96:99]
	v_mfma_f32_16x16x4_f32 v[100:103], v20, v42, v[100:103]
	v_mfma_f32_16x16x4_f32 v[88:91], v21, v31, v[88:91]
	v_mfma_f32_16x16x4_f32 v[92:95], v21, v35, v[92:95]
	v_mfma_f32_16x16x4_f32 v[96:99], v21, v39, v[96:99]
	v_mfma_f32_16x16x4_f32 v[100:103], v21, v43, v[100:103]
	v_mfma_f32_16x16x4_f32 v[88:91], v22, v32, v[88:91]
	v_mfma_f32_16x16x4_f32 v[92:95], v22, v36, v[92:95]
	v_mfma_f32_16x16x4_f32 v[96:99], v22, v40, v[96:99]
	v_mfma_f32_16x16x4_f32 v[100:103], v22, v44, v[100:103]
	v_mfma_f32_16x16x4_f32 v[88:91], v23, v33, v[88:91]
	v_mfma_f32_16x16x4_f32 v[92:95], v23, v37, v[92:95]
	v_mfma_f32_16x16x4_f32 v[96:99], v23, v41, v[96:99]
	v_mfma_f32_16x16x4_f32 v[100:103], v23, v45, v[100:103]
	s_waitcnt lgkmcnt(15)
	v_mfma_f32_16x16x4_f32 v[88:91], v24, v46, v[88:91]
	v_mfma_f32_16x16x4_f32 v[92:95], v24, v50, v[92:95]
	v_mfma_f32_16x16x4_f32 v[96:99], v24, v54, v[96:99]
	v_mfma_f32_16x16x4_f32 v[100:103], v24, v58, v[100:103]
	v_mfma_f32_16x16x4_f32 v[88:91], v25, v47, v[88:91]
	v_mfma_f32_16x16x4_f32 v[92:95], v25, v51, v[92:95]
	v_mfma_f32_16x16x4_f32 v[96:99], v25, v55, v[96:99]
	v_mfma_f32_16x16x4_f32 v[100:103], v25, v59, v[100:103]
	v_mfma_f32_16x16x4_f32 v[88:91], v26, v48, v[88:91]
	v_mfma_f32_16x16x4_f32 v[92:95], v26, v52, v[92:95]
	v_mfma_f32_16x16x4_f32 v[96:99], v26, v56, v[96:99]
	v_mfma_f32_16x16x4_f32 v[100:103], v26, v60, v[100:103]
	v_mfma_f32_16x16x4_f32 v[88:91], v27, v49, v[88:91]
	v_mfma_f32_16x16x4_f32 v[92:95], v27, v53, v[92:95]
	v_mfma_f32_16x16x4_f32 v[96:99], v27, v57, v[96:99]
	v_mfma_f32_16x16x4_f32 v[100:103], v27, v61, v[100:103]
	s_nop 9
	v_mfma_f32_16x16x4_f32 v[62:65], v178, v88, 0
	v_mfma_f32_16x16x4_f32 v[62:65], v179, v89, v[62:65]
	v_mfma_f32_16x16x4_f32 v[62:65], v180, v90, v[62:65]
	v_mfma_f32_16x16x4_f32 v[62:65], v181, v91, v[62:65]
	v_mfma_f32_16x16x4_f32 v[66:69], v178, v92, 0
	v_mfma_f32_16x16x4_f32 v[66:69], v179, v93, v[66:69]
	v_mfma_f32_16x16x4_f32 v[66:69], v180, v94, v[66:69]
	v_mfma_f32_16x16x4_f32 v[66:69], v181, v95, v[66:69]
	v_mfma_f32_16x16x4_f32 v[70:73], v178, v96, 0
	v_mfma_f32_16x16x4_f32 v[70:73], v179, v97, v[70:73]
	v_mfma_f32_16x16x4_f32 v[70:73], v180, v98, v[70:73]
	v_mfma_f32_16x16x4_f32 v[70:73], v181, v99, v[70:73]
	v_mfma_f32_16x16x4_f32 v[74:77], v178, v100, 0
	v_mfma_f32_16x16x4_f32 v[74:77], v179, v101, v[74:77]
	v_mfma_f32_16x16x4_f32 v[74:77], v180, v102, v[74:77]
	v_mfma_f32_16x16x4_f32 v[74:77], v181, v103, v[74:77]
	s_nop 9
	ds_write_b32 v167, v62 offset:16896
	ds_write_b32 v167, v63 offset:17424
	ds_write_b32 v167, v64 offset:17952
	ds_write_b32 v167, v65 offset:18480
	ds_write_b32 v167, v66 offset:16960
	ds_write_b32 v167, v67 offset:17488
	ds_write_b32 v167, v68 offset:18016
	ds_write_b32 v167, v69 offset:18544
	ds_write_b32 v167, v70 offset:17024
	ds_write_b32 v167, v71 offset:17552
	ds_write_b32 v167, v72 offset:18080
	ds_write_b32 v167, v73 offset:18608
	ds_write_b32 v167, v74 offset:17088
	ds_write_b32 v167, v75 offset:17616
	ds_write_b32 v167, v76 offset:18144
	ds_write_b32 v167, v77 offset:18672
	s_waitcnt lgkmcnt(0)
	v_mul_f32_e64 v104, -v192, v104
	v_mul_f32_e64 v105, -v193, v105
	v_mul_f32_e64 v106, -v194, v106
	v_mul_f32_e64 v107, -v195, v107
	v_mul_f32_e64 v108, -v192, v108
	v_mul_f32_e64 v109, -v193, v109
	v_mul_f32_e64 v110, -v194, v110
	v_mul_f32_e64 v111, -v195, v111
	v_mul_f32_e64 v112, -v192, v112
	v_mul_f32_e64 v113, -v193, v113
	v_mul_f32_e64 v114, -v194, v114
	v_mul_f32_e64 v115, -v195, v115
	v_mul_f32_e64 v116, -v192, v116
	v_mul_f32_e64 v117, -v193, v117
	v_mul_f32_e64 v118, -v194, v118
	v_mul_f32_e64 v119, -v195, v119
	ds_read_b128 v[20:23], v2 offset:13056
	ds_read_b128 v[24:27], v2 offset:13120
	ds_read_b128 v[146:149], v2 offset:13184
	s_waitcnt lgkmcnt(2)
	v_mfma_f32_16x16x4_f32 v[104:107], v20, v30, v[104:107]
	v_mfma_f32_16x16x4_f32 v[108:111], v20, v34, v[108:111]
	v_mfma_f32_16x16x4_f32 v[112:115], v20, v38, v[112:115]
	v_mfma_f32_16x16x4_f32 v[116:119], v20, v42, v[116:119]
	v_mfma_f32_16x16x4_f32 v[104:107], v21, v31, v[104:107]
	v_mfma_f32_16x16x4_f32 v[108:111], v21, v35, v[108:111]
	v_mfma_f32_16x16x4_f32 v[112:115], v21, v39, v[112:115]
	v_mfma_f32_16x16x4_f32 v[116:119], v21, v43, v[116:119]
	v_mfma_f32_16x16x4_f32 v[104:107], v22, v32, v[104:107]
	v_mfma_f32_16x16x4_f32 v[108:111], v22, v36, v[108:111]
	v_mfma_f32_16x16x4_f32 v[112:115], v22, v40, v[112:115]
	v_mfma_f32_16x16x4_f32 v[116:119], v22, v44, v[116:119]
	v_mfma_f32_16x16x4_f32 v[104:107], v23, v33, v[104:107]
	v_mfma_f32_16x16x4_f32 v[108:111], v23, v37, v[108:111]
	v_mfma_f32_16x16x4_f32 v[112:115], v23, v41, v[112:115]
	v_mfma_f32_16x16x4_f32 v[116:119], v23, v45, v[116:119]
	s_waitcnt lgkmcnt(1)
	v_mfma_f32_16x16x4_f32 v[104:107], v24, v46, v[104:107]
	v_mfma_f32_16x16x4_f32 v[108:111], v24, v50, v[108:111]
	v_mfma_f32_16x16x4_f32 v[112:115], v24, v54, v[112:115]
	v_mfma_f32_16x16x4_f32 v[116:119], v24, v58, v[116:119]
	v_mfma_f32_16x16x4_f32 v[104:107], v25, v47, v[104:107]
	v_mfma_f32_16x16x4_f32 v[108:111], v25, v51, v[108:111]
	v_mfma_f32_16x16x4_f32 v[112:115], v25, v55, v[112:115]
	v_mfma_f32_16x16x4_f32 v[116:119], v25, v59, v[116:119]
	v_mfma_f32_16x16x4_f32 v[104:107], v26, v48, v[104:107]
	v_mfma_f32_16x16x4_f32 v[108:111], v26, v52, v[108:111]
	v_mfma_f32_16x16x4_f32 v[112:115], v26, v56, v[112:115]
	v_mfma_f32_16x16x4_f32 v[116:119], v26, v60, v[116:119]
	v_mfma_f32_16x16x4_f32 v[104:107], v27, v49, v[104:107]
	v_mfma_f32_16x16x4_f32 v[108:111], v27, v53, v[108:111]
	v_mfma_f32_16x16x4_f32 v[112:115], v27, v57, v[112:115]
	v_mfma_f32_16x16x4_f32 v[116:119], v27, v61, v[116:119]
	s_waitcnt lgkmcnt(0)
	v_mfma_f32_16x16x4_f32 v[104:107], v146, v62, v[104:107]
	v_mfma_f32_16x16x4_f32 v[108:111], v146, v66, v[108:111]
	v_mfma_f32_16x16x4_f32 v[112:115], v146, v70, v[112:115]
	v_mfma_f32_16x16x4_f32 v[116:119], v146, v74, v[116:119]
	v_mfma_f32_16x16x4_f32 v[104:107], v147, v63, v[104:107]
	v_mfma_f32_16x16x4_f32 v[108:111], v147, v67, v[108:111]
	v_mfma_f32_16x16x4_f32 v[112:115], v147, v71, v[112:115]
	v_mfma_f32_16x16x4_f32 v[116:119], v147, v75, v[116:119]
	v_mfma_f32_16x16x4_f32 v[104:107], v148, v64, v[104:107]
	v_mfma_f32_16x16x4_f32 v[108:111], v148, v68, v[108:111]
	v_mfma_f32_16x16x4_f32 v[112:115], v148, v72, v[112:115]
	v_mfma_f32_16x16x4_f32 v[116:119], v148, v76, v[116:119]
	v_mfma_f32_16x16x4_f32 v[104:107], v149, v65, v[104:107]
	v_mfma_f32_16x16x4_f32 v[108:111], v149, v69, v[108:111]
	v_mfma_f32_16x16x4_f32 v[112:115], v149, v73, v[112:115]
	v_mfma_f32_16x16x4_f32 v[116:119], v149, v77, v[116:119]
	s_nop 9
	v_mfma_f32_16x16x4_f32 v[4:7], v188, v104, 0
	v_mfma_f32_16x16x4_f32 v[4:7], v189, v105, v[4:7]
	v_mfma_f32_16x16x4_f32 v[4:7], v190, v106, v[4:7]
	v_mfma_f32_16x16x4_f32 v[4:7], v191, v107, v[4:7]
	v_mfma_f32_16x16x4_f32 v[8:11], v188, v108, 0
	v_mfma_f32_16x16x4_f32 v[8:11], v189, v109, v[8:11]
	v_mfma_f32_16x16x4_f32 v[8:11], v190, v110, v[8:11]
	v_mfma_f32_16x16x4_f32 v[8:11], v191, v111, v[8:11]
	v_mfma_f32_16x16x4_f32 v[12:15], v188, v112, 0
	v_mfma_f32_16x16x4_f32 v[12:15], v189, v113, v[12:15]
	v_mfma_f32_16x16x4_f32 v[12:15], v190, v114, v[12:15]
	v_mfma_f32_16x16x4_f32 v[12:15], v191, v115, v[12:15]
	v_mfma_f32_16x16x4_f32 v[16:19], v188, v116, 0
	v_mfma_f32_16x16x4_f32 v[16:19], v189, v117, v[16:19]
	v_mfma_f32_16x16x4_f32 v[16:19], v190, v118, v[16:19]
	v_mfma_f32_16x16x4_f32 v[16:19], v191, v119, v[16:19]
	s_nop 9
	ds_write_b32 v167, v4 offset:25344
	ds_write_b32 v167, v5 offset:25872
	ds_write_b32 v167, v6 offset:26400
	ds_write_b32 v167, v7 offset:26928
	ds_write_b32 v167, v8 offset:25408
	ds_write_b32 v167, v9 offset:25936
	ds_write_b32 v167, v10 offset:26464
	ds_write_b32 v167, v11 offset:26992
	ds_write_b32 v167, v12 offset:25472
	ds_write_b32 v167, v13 offset:26000
	ds_write_b32 v167, v14 offset:26528
	ds_write_b32 v167, v15 offset:27056
	ds_write_b32 v167, v16 offset:25536
	ds_write_b32 v167, v17 offset:26064
	ds_write_b32 v167, v18 offset:26592
	ds_write_b32 v167, v19 offset:27120
	s_setprio 0
	s_branch .LBB0_174
